# hand-written W_out (P4) epilogue: residual loads issued three row groups ahead so waits do not sit behind earlier groups atomics; same arithmetic
# speedup vs baseline: 1.0042x; 1.0011x over previous
;     __device__ __forceinline__ void operator()(const f32x4 (&acc)[2][2][4][2], const Unit& u, int wr, int wc, int fr, int fq) const {
;         const int row0 = u.pm * BM + wr * 64 + fr, col0 = u.pn * BM + wc * 32 + 8 * fq;
;         float rs[8];
; #pragma unroll
;         for (int st = 0; st < 8; ++st) rs[st] = rs1[row0 + (st >> 2) * HALF + (st & 3) * 16];
;         u32x4 pre[2][2];
;         { const size_t off = (size_t)row0 * 1024 + col0; pre[0][0] = *(const u32x4*)(xb + off); pre[0][1] = *(const u32x4*)(xb + off + HALF); }
; #pragma unroll
;         for (int st = 0; st < 8; ++st) { const int ai = st >> 2, m = st & 3; const int row = row0 + ai * HALF + m * 16;
;             if (st < 7) { const int rn = row0 + ((st + 1) >> 2) * HALF + ((st + 1) & 3) * 16; const size_t off = (size_t)rn * 1024 + col0; u32x4* p = pre[(st + 1) & 1];
;                 p[0] = *(const u32x4*)(xb + off); p[1] = *(const u32x4*)(xb + off + HALF); }
;             __builtin_amdgcn_sched_barrier(0);
;             float s = 0.f; const float r = rs[st];
; #pragma unroll
;             for (int bj = 0; bj < 2; ++bj) { const size_t off = (size_t)row * 1024 + col0 + bj * HALF; const u32x4 h = pre[st & 1][bj];
;                 const f32x4 x0 = (f32x4){__uint_as_float(h.x << 16), __uint_as_float(h.x & 0xffff0000u), __uint_as_float(h.y << 16), __uint_as_float(h.y & 0xffff0000u)};
;                 const f32x4 x1v = (f32x4){__uint_as_float(h.z << 16), __uint_as_float(h.z & 0xffff0000u), __uint_as_float(h.w << 16), __uint_as_float(h.w & 0xffff0000u)};
;                 const f32x4 v0 = acc[ai][bj][m][0] + x0 * r, v1 = acc[ai][bj][m][1] + x1v * r;
;                 u32x4 w; w.x = cvt_pk_bf16(v0[0], v0[1]); w.y = cvt_pk_bf16(v0[2], v0[3]); w.z = cvt_pk_bf16(v1[0], v1[1]); w.w = cvt_pk_bf16(v1[2], v1[3]);
;                 *(u32x4*)(xb + off) = w;
;                 s += (v0[0] * v0[0] + v0[1] * v0[1]) + (v0[2] * v0[2] + v0[3] * v0[3]) + (v1[0] * v1[0] + v1[1] * v1[1]) + (v1[2] * v1[2] + v1[3] * v1[3]); }
;             s += __shfl_xor(s, 16); s += __shfl_xor(s, 32);
;             if (fq == 0) (void)__hip_atomic_fetch_add(racc + row, (1ull << 48) + (unsigned long long)(s * 65536.0f + 0.5f), __ATOMIC_RELAXED, __HIP_MEMORY_SCOPE_AGENT);
.LBB0_483:
	v_lshl_add_u32 v160, s52, 8, v155
	v_lshl_or_b32 v162, s50, 8, v165
	v_ashrrev_i32_e32 v161, 31, v160
	v_ashrrev_i32_e32 v163, 31, v162
	v_lshl_add_u64 v[180:181], v[160:161], 2, s[8:9]
	v_lshlrev_b64 v[172:173], 11, v[160:161]
	v_lshlrev_b64 v[162:163], 1, v[162:163]
	v_lshl_add_u64 v[172:173], s[36:37], 0, v[172:173]
	v_lshl_add_u64 v[178:179], v[160:161], 3, s[10:11]
	v_lshl_add_u64 v[172:173], v[172:173], 0, v[162:163]
	s_mov_b64 s[50:51], 0x8000
	v_mov_b64_e32 v[174:175], v[172:173]
	global_load_dwordx4 v[184:187], v[172:173], off
	global_load_dwordx4 v[188:191], v[172:173], off offset:256
	global_load_dword v164, v[180:181], off
	global_load_dword v166, v[180:181], off offset:64
	global_load_dword v170, v[180:181], off offset:128
	global_load_dword v176, v[180:181], off offset:192
	global_load_dword v182, v[180:181], off offset:512
	global_load_dword v152, v[180:181], off offset:576
	global_load_dword v154, v[180:181], off offset:640
	global_load_dword v158, v[180:181], off offset:704
	v_lshl_add_u64 v[172:173], v[172:173], 0, s[50:51]
	global_load_dwordx4 v[192:195], v[172:173], off
	global_load_dwordx4 v[196:199], v[172:173], off offset:256
	v_lshl_add_u64 v[172:173], v[172:173], 0, s[50:51]
	global_load_dwordx4 v[128:131], v[172:173], off
	global_load_dwordx4 v[132:135], v[172:173], off offset:256
	v_lshl_add_u64 v[172:173], v[172:173], 0, s[50:51]
	v_xor_b32_e32 v156, 16, v183
	v_xor_b32_e32 v157, 32, v183
	v_lshlrev_b32_e32 v156, 2, v156
	v_lshlrev_b32_e32 v157, 2, v157
	s_waitcnt vmcnt(4)
	v_lshlrev_b32_e32 v160, 16, v185
	v_and_b32_e32 v161, 0xffff0000, v185
	v_and_b32_e32 v185, 0xffff0000, v184
	v_lshlrev_b32_e32 v184, 16, v184
	v_lshlrev_b32_e32 v162, 16, v187
	v_and_b32_e32 v163, 0xffff0000, v187
	v_and_b32_e32 v187, 0xffff0000, v186
	v_lshlrev_b32_e32 v186, 16, v186
	v_pk_fma_f32 v[124:125], v[164:165], v[184:185], v[124:125] op_sel_hi:[0,1,1]
	v_pk_fma_f32 v[126:127], v[164:165], v[160:161], v[126:127] op_sel_hi:[0,1,1]
	v_pk_fma_f32 v[120:121], v[164:165], v[186:187], v[120:121] op_sel_hi:[0,1,1]
	v_pk_fma_f32 v[122:123], v[164:165], v[162:163], v[122:123] op_sel_hi:[0,1,1]
	v_mul_f32_e32 v168, v125, v125
	v_mul_f32_e32 v169, v127, v127
	v_fmac_f32_e32 v168, v124, v124
	v_fmac_f32_e32 v169, v126, v126
	v_add_f32_e32 v168, v168, v169
	v_mul_f32_e32 v169, v121, v121
	v_fmac_f32_e32 v169, v120, v120
	v_add_f32_e32 v168, v169, v168
	v_mul_f32_e32 v169, v123, v123
	v_fmac_f32_e32 v169, v122, v122
	v_add_f32_e32 v153, v169, v168
	v_cvt_pk_bf16_f32 v184, v124, v125
	v_cvt_pk_bf16_f32 v185, v126, v127
	v_cvt_pk_bf16_f32 v186, v120, v121
	v_cvt_pk_bf16_f32 v187, v122, v123
	global_store_dwordx4 v[174:175], v[184:187], off
	v_lshlrev_b32_e32 v160, 16, v189
	v_and_b32_e32 v161, 0xffff0000, v189
	v_and_b32_e32 v189, 0xffff0000, v188
	v_lshlrev_b32_e32 v188, 16, v188
	v_lshlrev_b32_e32 v162, 16, v191
	v_and_b32_e32 v163, 0xffff0000, v191
	v_and_b32_e32 v191, 0xffff0000, v190
	v_lshlrev_b32_e32 v190, 16, v190
	v_pk_fma_f32 v[116:117], v[164:165], v[188:189], v[116:117] op_sel_hi:[0,1,1]
	v_pk_fma_f32 v[118:119], v[164:165], v[160:161], v[118:119] op_sel_hi:[0,1,1]
	v_pk_fma_f32 v[112:113], v[164:165], v[190:191], v[112:113] op_sel_hi:[0,1,1]
	v_pk_fma_f32 v[114:115], v[164:165], v[162:163], v[114:115] op_sel_hi:[0,1,1]
	v_mul_f32_e32 v168, v117, v117
	v_mul_f32_e32 v169, v119, v119
	v_fmac_f32_e32 v168, v116, v116
	v_fmac_f32_e32 v169, v118, v118
	v_add_f32_e32 v168, v168, v169
	v_mul_f32_e32 v169, v113, v113
	v_fmac_f32_e32 v169, v112, v112
	v_add_f32_e32 v168, v169, v168
	v_mul_f32_e32 v169, v115, v115
	v_fmac_f32_e32 v169, v114, v114
	v_add_f32_e32 v180, v169, v168
	v_cvt_pk_bf16_f32 v188, v116, v117
	v_cvt_pk_bf16_f32 v189, v118, v119
	v_cvt_pk_bf16_f32 v190, v112, v113
	v_cvt_pk_bf16_f32 v191, v114, v115
	global_store_dwordx4 v[174:175], v[188:191], off offset:256
	v_add_f32_e32 v180, v153, v180
	ds_bpermute_b32 v169, v156, v180
	global_load_dwordx4 v[124:127], v[172:173], off
	global_load_dwordx4 v[116:119], v[172:173], off offset:256
	s_mov_b64 s[50:51], 0x28000
	v_lshl_add_u64 v[172:173], v[172:173], 0, s[50:51]
	s_mov_b64 s[50:51], 0x8000
	v_lshl_add_u64 v[174:175], v[174:175], 0, s[50:51]
	s_waitcnt lgkmcnt(0)
	v_add_f32_e32 v180, v180, v169
	ds_bpermute_b32 v169, v157, v180
	s_waitcnt lgkmcnt(0)
	s_and_saveexec_b64 vcc, s[2:3]
	v_add_f32_e32 v180, v180, v169
	v_fma_f32 v180, v180, s66, 0.5
	v_trunc_f32_e32 v180, v180
	v_mul_f32_e32 v181, 0x2f800000, v180
	v_floor_f32_e32 v181, v181
	v_fmac_f32_e32 v180, 0xcf800000, v181
	v_cvt_u32_f32_e32 v181, v181
	v_cvt_u32_f32_e32 v180, v180
	v_add_u32_e32 v181, 0x10000, v181
	global_atomic_add_x2 v[178:179], v[180:181], off
	s_mov_b64 exec, vcc
	s_waitcnt vmcnt(7)
; __device__ __forceinline__ unsigned cvt_pk_bf16(float lo, float hi) { unsigned r; asm volatile("v_cvt_pk_bf16_f32 %0, %1, %2" : "=v"(r) : "v"(lo), "v"(hi)); return r; }
;     __device__ __forceinline__ void operator()(const f32x4 (&acc)[2][2][4][2], const Unit& u, int wr, int wc, int fr, int fq) const {
;     ...
;         for (int st = 0; st < 8; ++st) { const int ai = st >> 2, m = st & 3; const int row = row0 + ai * HALF + m * 16;
;             if (st < 7) { const int rn = row0 + ((st + 1) >> 2) * HALF + ((st + 1) & 3) * 16; const size_t off = (size_t)rn * 1024 + col0; u32x4* p = pre[(st + 1) & 1];
;                 p[0] = *(const u32x4*)(xb + off); p[1] = *(const u32x4*)(xb + off + HALF); }
;             __builtin_amdgcn_sched_barrier(0);
;             float s = 0.f; const float r = rs[st];
; #pragma unroll
;             for (int bj = 0; bj < 2; ++bj) { const size_t off = (size_t)row * 1024 + col0 + bj * HALF; const u32x4 h = pre[st & 1][bj];
;                 const f32x4 x0 = (f32x4){__uint_as_float(h.x << 16), __uint_as_float(h.x & 0xffff0000u), __uint_as_float(h.y << 16), __uint_as_float(h.y & 0xffff0000u)};
;                 const f32x4 x1v = (f32x4){__uint_as_float(h.z << 16), __uint_as_float(h.z & 0xffff0000u), __uint_as_float(h.w << 16), __uint_as_float(h.w & 0xffff0000u)};
;                 const f32x4 v0 = acc[ai][bj][m][0] + x0 * r, v1 = acc[ai][bj][m][1] + x1v * r;
;                 u32x4 w; w.x = cvt_pk_bf16(v0[0], v0[1]); w.y = cvt_pk_bf16(v0[2], v0[3]); w.z = cvt_pk_bf16(v1[0], v1[1]); w.w = cvt_pk_bf16(v1[2], v1[3]);
;                 *(u32x4*)(xb + off) = w;
;                 s += (v0[0] * v0[0] + v0[1] * v0[1]) + (v0[2] * v0[2] + v0[3] * v0[3]) + (v1[0] * v1[0] + v1[1] * v1[1]) + (v1[2] * v1[2] + v1[3] * v1[3]); }
;             s += __shfl_xor(s, 16); s += __shfl_xor(s, 32);
;             if (fq == 0) (void)__hip_atomic_fetch_add(racc + row, (1ull << 48) + (unsigned long long)(s * 65536.0f + 0.5f), __ATOMIC_RELAXED, __HIP_MEMORY_SCOPE_AGENT);
	v_lshlrev_b32_e32 v160, 16, v193
	v_and_b32_e32 v161, 0xffff0000, v193
	v_and_b32_e32 v193, 0xffff0000, v192
	v_lshlrev_b32_e32 v192, 16, v192
	v_lshlrev_b32_e32 v162, 16, v195
	v_and_b32_e32 v163, 0xffff0000, v195
	v_and_b32_e32 v195, 0xffff0000, v194
	v_lshlrev_b32_e32 v194, 16, v194
	v_pk_fma_f32 v[108:109], v[166:167], v[192:193], v[108:109] op_sel_hi:[0,1,1]
	v_pk_fma_f32 v[110:111], v[166:167], v[160:161], v[110:111] op_sel_hi:[0,1,1]
	v_pk_fma_f32 v[104:105], v[166:167], v[194:195], v[104:105] op_sel_hi:[0,1,1]
	v_pk_fma_f32 v[106:107], v[166:167], v[162:163], v[106:107] op_sel_hi:[0,1,1]
	v_mul_f32_e32 v168, v109, v109
	v_mul_f32_e32 v169, v111, v111
	v_fmac_f32_e32 v168, v108, v108
	v_fmac_f32_e32 v169, v110, v110
	v_add_f32_e32 v168, v168, v169
	v_mul_f32_e32 v169, v105, v105
	v_fmac_f32_e32 v169, v104, v104
	v_add_f32_e32 v168, v169, v168
	v_mul_f32_e32 v169, v107, v107
	v_fmac_f32_e32 v169, v106, v106
	v_add_f32_e32 v153, v169, v168
	v_cvt_pk_bf16_f32 v192, v108, v109
	v_cvt_pk_bf16_f32 v193, v110, v111
	v_cvt_pk_bf16_f32 v194, v104, v105
	v_cvt_pk_bf16_f32 v195, v106, v107
	global_store_dwordx4 v[174:175], v[192:195], off
	v_lshlrev_b32_e32 v160, 16, v197
	v_and_b32_e32 v161, 0xffff0000, v197
	v_and_b32_e32 v197, 0xffff0000, v196
	v_lshlrev_b32_e32 v196, 16, v196
	v_lshlrev_b32_e32 v162, 16, v199
	v_and_b32_e32 v163, 0xffff0000, v199
	v_and_b32_e32 v199, 0xffff0000, v198
	v_lshlrev_b32_e32 v198, 16, v198
	v_pk_fma_f32 v[100:101], v[166:167], v[196:197], v[100:101] op_sel_hi:[0,1,1]
	v_pk_fma_f32 v[102:103], v[166:167], v[160:161], v[102:103] op_sel_hi:[0,1,1]
	v_pk_fma_f32 v[96:97], v[166:167], v[198:199], v[96:97] op_sel_hi:[0,1,1]
	v_pk_fma_f32 v[98:99], v[166:167], v[162:163], v[98:99] op_sel_hi:[0,1,1]
	v_mul_f32_e32 v168, v101, v101
	v_mul_f32_e32 v169, v103, v103
	v_fmac_f32_e32 v168, v100, v100
	v_fmac_f32_e32 v169, v102, v102
	v_add_f32_e32 v168, v168, v169
	v_mul_f32_e32 v169, v97, v97
	v_fmac_f32_e32 v169, v96, v96
	v_add_f32_e32 v168, v169, v168
	v_mul_f32_e32 v169, v99, v99
	v_fmac_f32_e32 v169, v98, v98
	v_add_f32_e32 v180, v169, v168
	v_cvt_pk_bf16_f32 v196, v100, v101
	v_cvt_pk_bf16_f32 v197, v102, v103
	v_cvt_pk_bf16_f32 v198, v96, v97
	v_cvt_pk_bf16_f32 v199, v98, v99
	global_store_dwordx4 v[174:175], v[196:199], off offset:256
	v_add_f32_e32 v180, v153, v180
	ds_bpermute_b32 v169, v156, v180
	global_load_dwordx4 v[108:111], v[172:173], off
	global_load_dwordx4 v[100:103], v[172:173], off offset:256
	v_lshl_add_u64 v[172:173], v[172:173], 0, s[50:51]
	v_lshl_add_u64 v[174:175], v[174:175], 0, s[50:51]
	s_waitcnt lgkmcnt(0)
	v_add_f32_e32 v180, v180, v169
	ds_bpermute_b32 v169, v157, v180
	s_waitcnt lgkmcnt(0)
	s_and_saveexec_b64 vcc, s[2:3]
	v_add_f32_e32 v180, v180, v169
	v_fma_f32 v180, v180, s66, 0.5
	v_trunc_f32_e32 v180, v180
	v_mul_f32_e32 v181, 0x2f800000, v180
	v_floor_f32_e32 v181, v181
	v_fmac_f32_e32 v180, 0xcf800000, v181
	v_cvt_u32_f32_e32 v181, v181
	v_cvt_u32_f32_e32 v180, v180
	v_add_u32_e32 v181, 0x10000, v181
	global_atomic_add_x2 v[178:179], v[180:181], off offset:128
	s_mov_b64 exec, vcc
	s_waitcnt vmcnt(10)
	v_lshlrev_b32_e32 v160, 16, v129
	v_and_b32_e32 v161, 0xffff0000, v129
	v_and_b32_e32 v129, 0xffff0000, v128
	v_lshlrev_b32_e32 v128, 16, v128
	v_lshlrev_b32_e32 v162, 16, v131
	v_and_b32_e32 v163, 0xffff0000, v131
	v_and_b32_e32 v131, 0xffff0000, v130
	v_lshlrev_b32_e32 v130, 16, v130
	v_pk_fma_f32 v[92:93], v[170:171], v[128:129], v[92:93] op_sel_hi:[0,1,1]
	v_pk_fma_f32 v[94:95], v[170:171], v[160:161], v[94:95] op_sel_hi:[0,1,1]
	v_pk_fma_f32 v[88:89], v[170:171], v[130:131], v[88:89] op_sel_hi:[0,1,1]
	v_pk_fma_f32 v[90:91], v[170:171], v[162:163], v[90:91] op_sel_hi:[0,1,1]
	v_mul_f32_e32 v168, v93, v93
	v_mul_f32_e32 v169, v95, v95
	v_fmac_f32_e32 v168, v92, v92
	v_fmac_f32_e32 v169, v94, v94
	v_add_f32_e32 v168, v168, v169
	v_mul_f32_e32 v169, v89, v89
	v_fmac_f32_e32 v169, v88, v88
	v_add_f32_e32 v168, v169, v168
	v_mul_f32_e32 v169, v91, v91
	v_fmac_f32_e32 v169, v90, v90
	v_add_f32_e32 v153, v169, v168
	v_cvt_pk_bf16_f32 v128, v92, v93
	v_cvt_pk_bf16_f32 v129, v94, v95
	v_cvt_pk_bf16_f32 v130, v88, v89
	v_cvt_pk_bf16_f32 v131, v90, v91
	global_store_dwordx4 v[174:175], v[128:131], off
	v_lshlrev_b32_e32 v160, 16, v133
	v_and_b32_e32 v161, 0xffff0000, v133
	v_and_b32_e32 v133, 0xffff0000, v132
	v_lshlrev_b32_e32 v132, 16, v132
	v_lshlrev_b32_e32 v162, 16, v135
	v_and_b32_e32 v163, 0xffff0000, v135
	v_and_b32_e32 v135, 0xffff0000, v134
	v_lshlrev_b32_e32 v134, 16, v134
	v_pk_fma_f32 v[84:85], v[170:171], v[132:133], v[84:85] op_sel_hi:[0,1,1]
	v_pk_fma_f32 v[86:87], v[170:171], v[160:161], v[86:87] op_sel_hi:[0,1,1]
	v_pk_fma_f32 v[80:81], v[170:171], v[134:135], v[80:81] op_sel_hi:[0,1,1]
	v_pk_fma_f32 v[82:83], v[170:171], v[162:163], v[82:83] op_sel_hi:[0,1,1]
	v_mul_f32_e32 v168, v85, v85
	v_mul_f32_e32 v169, v87, v87
	v_fmac_f32_e32 v168, v84, v84
	v_fmac_f32_e32 v169, v86, v86
	v_add_f32_e32 v168, v168, v169
	v_mul_f32_e32 v169, v81, v81
	v_fmac_f32_e32 v169, v80, v80
	v_add_f32_e32 v168, v169, v168
	v_mul_f32_e32 v169, v83, v83
	v_fmac_f32_e32 v169, v82, v82
	v_add_f32_e32 v180, v169, v168
	v_cvt_pk_bf16_f32 v132, v84, v85
	v_cvt_pk_bf16_f32 v133, v86, v87
	v_cvt_pk_bf16_f32 v134, v80, v81
	v_cvt_pk_bf16_f32 v135, v82, v83
	global_store_dwordx4 v[174:175], v[132:135], off offset:256
	v_add_f32_e32 v180, v153, v180
	ds_bpermute_b32 v169, v156, v180
	global_load_dwordx4 v[92:95], v[172:173], off
	global_load_dwordx4 v[84:87], v[172:173], off offset:256
	v_lshl_add_u64 v[172:173], v[172:173], 0, s[50:51]
	v_lshl_add_u64 v[174:175], v[174:175], 0, s[50:51]
	s_waitcnt lgkmcnt(0)
; __device__ __forceinline__ unsigned cvt_pk_bf16(float lo, float hi) { unsigned r; asm volatile("v_cvt_pk_bf16_f32 %0, %1, %2" : "=v"(r) : "v"(lo), "v"(hi)); return r; }
;     __device__ __forceinline__ void operator()(const f32x4 (&acc)[2][2][4][2], const Unit& u, int wr, int wc, int fr, int fq) const {
;     ...
;         for (int st = 0; st < 8; ++st) { const int ai = st >> 2, m = st & 3; const int row = row0 + ai * HALF + m * 16;
;             if (st < 7) { const int rn = row0 + ((st + 1) >> 2) * HALF + ((st + 1) & 3) * 16; const size_t off = (size_t)rn * 1024 + col0; u32x4* p = pre[(st + 1) & 1];
;                 p[0] = *(const u32x4*)(xb + off); p[1] = *(const u32x4*)(xb + off + HALF); }
;             __builtin_amdgcn_sched_barrier(0);
;             float s = 0.f; const float r = rs[st];
; #pragma unroll
;             for (int bj = 0; bj < 2; ++bj) { const size_t off = (size_t)row * 1024 + col0 + bj * HALF; const u32x4 h = pre[st & 1][bj];
;                 const f32x4 x0 = (f32x4){__uint_as_float(h.x << 16), __uint_as_float(h.x & 0xffff0000u), __uint_as_float(h.y << 16), __uint_as_float(h.y & 0xffff0000u)};
;                 const f32x4 x1v = (f32x4){__uint_as_float(h.z << 16), __uint_as_float(h.z & 0xffff0000u), __uint_as_float(h.w << 16), __uint_as_float(h.w & 0xffff0000u)};
;                 const f32x4 v0 = acc[ai][bj][m][0] + x0 * r, v1 = acc[ai][bj][m][1] + x1v * r;
;                 u32x4 w; w.x = cvt_pk_bf16(v0[0], v0[1]); w.y = cvt_pk_bf16(v0[2], v0[3]); w.z = cvt_pk_bf16(v1[0], v1[1]); w.w = cvt_pk_bf16(v1[2], v1[3]);
;                 *(u32x4*)(xb + off) = w;
;                 s += (v0[0] * v0[0] + v0[1] * v0[1]) + (v0[2] * v0[2] + v0[3] * v0[3]) + (v1[0] * v1[0] + v1[1] * v1[1]) + (v1[2] * v1[2] + v1[3] * v1[3]); }
;             s += __shfl_xor(s, 16); s += __shfl_xor(s, 32);
;             if (fq == 0) (void)__hip_atomic_fetch_add(racc + row, (1ull << 48) + (unsigned long long)(s * 65536.0f + 0.5f), __ATOMIC_RELAXED, __HIP_MEMORY_SCOPE_AGENT);
	v_add_f32_e32 v180, v180, v169
	ds_bpermute_b32 v169, v157, v180
	s_waitcnt lgkmcnt(0)
	s_and_saveexec_b64 vcc, s[2:3]
	v_add_f32_e32 v180, v180, v169
	v_fma_f32 v180, v180, s66, 0.5
	v_trunc_f32_e32 v180, v180
	v_mul_f32_e32 v181, 0x2f800000, v180
	v_floor_f32_e32 v181, v181
	v_fmac_f32_e32 v180, 0xcf800000, v181
	v_cvt_u32_f32_e32 v181, v181
	v_cvt_u32_f32_e32 v180, v180
	v_add_u32_e32 v181, 0x10000, v181
	global_atomic_add_x2 v[178:179], v[180:181], off offset:256
	s_mov_b64 exec, vcc
	s_waitcnt vmcnt(11)
	v_lshlrev_b32_e32 v160, 16, v125
	v_and_b32_e32 v161, 0xffff0000, v125
	v_and_b32_e32 v125, 0xffff0000, v124
	v_lshlrev_b32_e32 v124, 16, v124
	v_lshlrev_b32_e32 v162, 16, v127
	v_and_b32_e32 v163, 0xffff0000, v127
	v_and_b32_e32 v127, 0xffff0000, v126
	v_lshlrev_b32_e32 v126, 16, v126
	v_pk_fma_f32 v[76:77], v[176:177], v[124:125], v[76:77] op_sel_hi:[0,1,1]
	v_pk_fma_f32 v[78:79], v[176:177], v[160:161], v[78:79] op_sel_hi:[0,1,1]
	v_pk_fma_f32 v[72:73], v[176:177], v[126:127], v[72:73] op_sel_hi:[0,1,1]
	v_pk_fma_f32 v[74:75], v[176:177], v[162:163], v[74:75] op_sel_hi:[0,1,1]
	v_mul_f32_e32 v168, v77, v77
	v_mul_f32_e32 v169, v79, v79
	v_fmac_f32_e32 v168, v76, v76
	v_fmac_f32_e32 v169, v78, v78
	v_add_f32_e32 v168, v168, v169
	v_mul_f32_e32 v169, v73, v73
	v_fmac_f32_e32 v169, v72, v72
	v_add_f32_e32 v168, v169, v168
	v_mul_f32_e32 v169, v75, v75
	v_fmac_f32_e32 v169, v74, v74
	v_add_f32_e32 v153, v169, v168
	v_cvt_pk_bf16_f32 v124, v76, v77
	v_cvt_pk_bf16_f32 v125, v78, v79
	v_cvt_pk_bf16_f32 v126, v72, v73
	v_cvt_pk_bf16_f32 v127, v74, v75
	global_store_dwordx4 v[174:175], v[124:127], off
	v_lshlrev_b32_e32 v160, 16, v117
	v_and_b32_e32 v161, 0xffff0000, v117
	v_and_b32_e32 v117, 0xffff0000, v116
	v_lshlrev_b32_e32 v116, 16, v116
	v_lshlrev_b32_e32 v162, 16, v119
	v_and_b32_e32 v163, 0xffff0000, v119
	v_and_b32_e32 v119, 0xffff0000, v118
	v_lshlrev_b32_e32 v118, 16, v118
	v_pk_fma_f32 v[68:69], v[176:177], v[116:117], v[68:69] op_sel_hi:[0,1,1]
	v_pk_fma_f32 v[70:71], v[176:177], v[160:161], v[70:71] op_sel_hi:[0,1,1]
	v_pk_fma_f32 v[64:65], v[176:177], v[118:119], v[64:65] op_sel_hi:[0,1,1]
	v_pk_fma_f32 v[66:67], v[176:177], v[162:163], v[66:67] op_sel_hi:[0,1,1]
	v_mul_f32_e32 v168, v69, v69
	v_mul_f32_e32 v169, v71, v71
	v_fmac_f32_e32 v168, v68, v68
	v_fmac_f32_e32 v169, v70, v70
	v_add_f32_e32 v168, v168, v169
	v_mul_f32_e32 v169, v65, v65
	v_fmac_f32_e32 v169, v64, v64
	v_add_f32_e32 v168, v169, v168
	v_mul_f32_e32 v169, v67, v67
	v_fmac_f32_e32 v169, v66, v66
	v_add_f32_e32 v180, v169, v168
	v_cvt_pk_bf16_f32 v116, v68, v69
	v_cvt_pk_bf16_f32 v117, v70, v71
	v_cvt_pk_bf16_f32 v118, v64, v65
	v_cvt_pk_bf16_f32 v119, v66, v67
	global_store_dwordx4 v[174:175], v[116:119], off offset:256
	v_add_f32_e32 v180, v153, v180
	ds_bpermute_b32 v169, v156, v180
	global_load_dwordx4 v[76:79], v[172:173], off
	global_load_dwordx4 v[68:71], v[172:173], off offset:256
	v_lshl_add_u64 v[172:173], v[172:173], 0, s[50:51]
	s_mov_b64 s[50:51], 0x28000
	v_lshl_add_u64 v[174:175], v[174:175], 0, s[50:51]
	s_mov_b64 s[50:51], 0x8000
	s_waitcnt lgkmcnt(0)
	v_add_f32_e32 v180, v180, v169
	ds_bpermute_b32 v169, v157, v180
	s_waitcnt lgkmcnt(0)
	s_and_saveexec_b64 vcc, s[2:3]
	v_add_f32_e32 v180, v180, v169
	v_fma_f32 v180, v180, s66, 0.5
	v_trunc_f32_e32 v180, v180
	v_mul_f32_e32 v181, 0x2f800000, v180
	v_floor_f32_e32 v181, v181
	v_fmac_f32_e32 v180, 0xcf800000, v181
	v_cvt_u32_f32_e32 v181, v181
	v_cvt_u32_f32_e32 v180, v180
	v_add_u32_e32 v181, 0x10000, v181
	global_atomic_add_x2 v[178:179], v[180:181], off offset:384
	s_mov_b64 exec, vcc
	s_waitcnt vmcnt(11)
	v_lshlrev_b32_e32 v160, 16, v109
	v_and_b32_e32 v161, 0xffff0000, v109
	v_and_b32_e32 v109, 0xffff0000, v108
	v_lshlrev_b32_e32 v108, 16, v108
	v_lshlrev_b32_e32 v162, 16, v111
	v_and_b32_e32 v163, 0xffff0000, v111
	v_and_b32_e32 v111, 0xffff0000, v110
	v_lshlrev_b32_e32 v110, 16, v110
	v_pk_fma_f32 v[60:61], v[182:183], v[108:109], v[60:61] op_sel_hi:[0,1,1]
	v_pk_fma_f32 v[62:63], v[182:183], v[160:161], v[62:63] op_sel_hi:[0,1,1]
	v_pk_fma_f32 v[56:57], v[182:183], v[110:111], v[56:57] op_sel_hi:[0,1,1]
	v_pk_fma_f32 v[58:59], v[182:183], v[162:163], v[58:59] op_sel_hi:[0,1,1]
	v_mul_f32_e32 v168, v61, v61
	v_mul_f32_e32 v169, v63, v63
	v_fmac_f32_e32 v168, v60, v60
	v_fmac_f32_e32 v169, v62, v62
	v_add_f32_e32 v168, v168, v169
	v_mul_f32_e32 v169, v57, v57
	v_fmac_f32_e32 v169, v56, v56
	v_add_f32_e32 v168, v169, v168
	v_mul_f32_e32 v169, v59, v59
	v_fmac_f32_e32 v169, v58, v58
	v_add_f32_e32 v153, v169, v168
	v_cvt_pk_bf16_f32 v108, v60, v61
	v_cvt_pk_bf16_f32 v109, v62, v63
	v_cvt_pk_bf16_f32 v110, v56, v57
	v_cvt_pk_bf16_f32 v111, v58, v59
	global_store_dwordx4 v[174:175], v[108:111], off
	v_lshlrev_b32_e32 v160, 16, v101
	v_and_b32_e32 v161, 0xffff0000, v101
	v_and_b32_e32 v101, 0xffff0000, v100
	v_lshlrev_b32_e32 v100, 16, v100
	v_lshlrev_b32_e32 v162, 16, v103
	v_and_b32_e32 v163, 0xffff0000, v103
	v_and_b32_e32 v103, 0xffff0000, v102
	v_lshlrev_b32_e32 v102, 16, v102
	v_pk_fma_f32 v[52:53], v[182:183], v[100:101], v[52:53] op_sel_hi:[0,1,1]
	v_pk_fma_f32 v[54:55], v[182:183], v[160:161], v[54:55] op_sel_hi:[0,1,1]
	v_pk_fma_f32 v[48:49], v[182:183], v[102:103], v[48:49] op_sel_hi:[0,1,1]
	v_pk_fma_f32 v[50:51], v[182:183], v[162:163], v[50:51] op_sel_hi:[0,1,1]
	v_mul_f32_e32 v168, v53, v53
	v_mul_f32_e32 v169, v55, v55
	v_fmac_f32_e32 v168, v52, v52
	v_fmac_f32_e32 v169, v54, v54
	v_add_f32_e32 v168, v168, v169
	v_mul_f32_e32 v169, v49, v49
	v_fmac_f32_e32 v169, v48, v48
	v_add_f32_e32 v168, v169, v168
	v_mul_f32_e32 v169, v51, v51
	v_fmac_f32_e32 v169, v50, v50
	v_add_f32_e32 v180, v169, v168
	v_cvt_pk_bf16_f32 v100, v52, v53
	v_cvt_pk_bf16_f32 v101, v54, v55
	v_cvt_pk_bf16_f32 v102, v48, v49
	v_cvt_pk_bf16_f32 v103, v50, v51
	global_store_dwordx4 v[174:175], v[100:103], off offset:256
	v_add_f32_e32 v180, v153, v180
	ds_bpermute_b32 v169, v156, v180
	global_load_dwordx4 v[60:63], v[172:173], off
	global_load_dwordx4 v[52:55], v[172:173], off offset:256
	v_lshl_add_u64 v[174:175], v[174:175], 0, s[50:51]
	s_waitcnt lgkmcnt(0)
; __device__ __forceinline__ unsigned cvt_pk_bf16(float lo, float hi) { unsigned r; asm volatile("v_cvt_pk_bf16_f32 %0, %1, %2" : "=v"(r) : "v"(lo), "v"(hi)); return r; }
;     __device__ __forceinline__ void operator()(const f32x4 (&acc)[2][2][4][2], const Unit& u, int wr, int wc, int fr, int fq) const {
;     ...
;         for (int st = 0; st < 8; ++st) { const int ai = st >> 2, m = st & 3; const int row = row0 + ai * HALF + m * 16;
;             if (st < 7) { const int rn = row0 + ((st + 1) >> 2) * HALF + ((st + 1) & 3) * 16; const size_t off = (size_t)rn * 1024 + col0; u32x4* p = pre[(st + 1) & 1];
;                 p[0] = *(const u32x4*)(xb + off); p[1] = *(const u32x4*)(xb + off + HALF); }
;             __builtin_amdgcn_sched_barrier(0);
;             float s = 0.f; const float r = rs[st];
; #pragma unroll
;             for (int bj = 0; bj < 2; ++bj) { const size_t off = (size_t)row * 1024 + col0 + bj * HALF; const u32x4 h = pre[st & 1][bj];
;                 const f32x4 x0 = (f32x4){__uint_as_float(h.x << 16), __uint_as_float(h.x & 0xffff0000u), __uint_as_float(h.y << 16), __uint_as_float(h.y & 0xffff0000u)};
;                 const f32x4 x1v = (f32x4){__uint_as_float(h.z << 16), __uint_as_float(h.z & 0xffff0000u), __uint_as_float(h.w << 16), __uint_as_float(h.w & 0xffff0000u)};
;                 const f32x4 v0 = acc[ai][bj][m][0] + x0 * r, v1 = acc[ai][bj][m][1] + x1v * r;
;                 u32x4 w; w.x = cvt_pk_bf16(v0[0], v0[1]); w.y = cvt_pk_bf16(v0[2], v0[3]); w.z = cvt_pk_bf16(v1[0], v1[1]); w.w = cvt_pk_bf16(v1[2], v1[3]);
;                 *(u32x4*)(xb + off) = w;
;                 s += (v0[0] * v0[0] + v0[1] * v0[1]) + (v0[2] * v0[2] + v0[3] * v0[3]) + (v1[0] * v1[0] + v1[1] * v1[1]) + (v1[2] * v1[2] + v1[3] * v1[3]); }
;             s += __shfl_xor(s, 16); s += __shfl_xor(s, 32);
;             if (fq == 0) (void)__hip_atomic_fetch_add(racc + row, (1ull << 48) + (unsigned long long)(s * 65536.0f + 0.5f), __ATOMIC_RELAXED, __HIP_MEMORY_SCOPE_AGENT);
	v_add_f32_e32 v180, v180, v169
	ds_bpermute_b32 v169, v157, v180
	s_waitcnt lgkmcnt(0)
	s_and_saveexec_b64 vcc, s[2:3]
	v_add_f32_e32 v180, v180, v169
	v_fma_f32 v180, v180, s66, 0.5
	v_trunc_f32_e32 v180, v180
	v_mul_f32_e32 v181, 0x2f800000, v180
	v_floor_f32_e32 v181, v181
	v_fmac_f32_e32 v180, 0xcf800000, v181
	v_cvt_u32_f32_e32 v181, v181
	v_cvt_u32_f32_e32 v180, v180
	v_add_u32_e32 v181, 0x10000, v181
	global_atomic_add_x2 v[178:179], v[180:181], off offset:1024
	s_mov_b64 exec, vcc
	s_waitcnt vmcnt(11)
	v_lshlrev_b32_e32 v160, 16, v93
	v_and_b32_e32 v161, 0xffff0000, v93
	v_and_b32_e32 v93, 0xffff0000, v92
	v_lshlrev_b32_e32 v92, 16, v92
	v_lshlrev_b32_e32 v162, 16, v95
	v_and_b32_e32 v163, 0xffff0000, v95
	v_and_b32_e32 v95, 0xffff0000, v94
	v_lshlrev_b32_e32 v94, 16, v94
	v_pk_fma_f32 v[44:45], v[152:153], v[92:93], v[44:45] op_sel_hi:[0,1,1]
	v_pk_fma_f32 v[46:47], v[152:153], v[160:161], v[46:47] op_sel_hi:[0,1,1]
	v_pk_fma_f32 v[40:41], v[152:153], v[94:95], v[40:41] op_sel_hi:[0,1,1]
	v_pk_fma_f32 v[42:43], v[152:153], v[162:163], v[42:43] op_sel_hi:[0,1,1]
	v_mul_f32_e32 v168, v45, v45
	v_mul_f32_e32 v169, v47, v47
	v_fmac_f32_e32 v168, v44, v44
	v_fmac_f32_e32 v169, v46, v46
	v_add_f32_e32 v168, v168, v169
	v_mul_f32_e32 v169, v41, v41
	v_fmac_f32_e32 v169, v40, v40
	v_add_f32_e32 v168, v169, v168
	v_mul_f32_e32 v169, v43, v43
	v_fmac_f32_e32 v169, v42, v42
	v_add_f32_e32 v153, v169, v168
	v_cvt_pk_bf16_f32 v92, v44, v45
	v_cvt_pk_bf16_f32 v93, v46, v47
	v_cvt_pk_bf16_f32 v94, v40, v41
	v_cvt_pk_bf16_f32 v95, v42, v43
	global_store_dwordx4 v[174:175], v[92:95], off
	v_lshlrev_b32_e32 v160, 16, v85
	v_and_b32_e32 v161, 0xffff0000, v85
	v_and_b32_e32 v85, 0xffff0000, v84
	v_lshlrev_b32_e32 v84, 16, v84
	v_lshlrev_b32_e32 v162, 16, v87
	v_and_b32_e32 v163, 0xffff0000, v87
	v_and_b32_e32 v87, 0xffff0000, v86
	v_lshlrev_b32_e32 v86, 16, v86
	v_pk_fma_f32 v[36:37], v[152:153], v[84:85], v[36:37] op_sel_hi:[0,1,1]
	v_pk_fma_f32 v[38:39], v[152:153], v[160:161], v[38:39] op_sel_hi:[0,1,1]
	v_pk_fma_f32 v[32:33], v[152:153], v[86:87], v[32:33] op_sel_hi:[0,1,1]
	v_pk_fma_f32 v[34:35], v[152:153], v[162:163], v[34:35] op_sel_hi:[0,1,1]
	v_mul_f32_e32 v168, v37, v37
	v_mul_f32_e32 v169, v39, v39
	v_fmac_f32_e32 v168, v36, v36
	v_fmac_f32_e32 v169, v38, v38
	v_add_f32_e32 v168, v168, v169
	v_mul_f32_e32 v169, v33, v33
	v_fmac_f32_e32 v169, v32, v32
	v_add_f32_e32 v168, v169, v168
	v_mul_f32_e32 v169, v35, v35
	v_fmac_f32_e32 v169, v34, v34
	v_add_f32_e32 v180, v169, v168
	v_cvt_pk_bf16_f32 v84, v36, v37
	v_cvt_pk_bf16_f32 v85, v38, v39
	v_cvt_pk_bf16_f32 v86, v32, v33
	v_cvt_pk_bf16_f32 v87, v34, v35
	global_store_dwordx4 v[174:175], v[84:87], off offset:256
	v_add_f32_e32 v180, v153, v180
	ds_bpermute_b32 v169, v156, v180
	v_lshl_add_u64 v[174:175], v[174:175], 0, s[50:51]
	s_waitcnt lgkmcnt(0)
	v_add_f32_e32 v180, v180, v169
	ds_bpermute_b32 v169, v157, v180
	s_waitcnt lgkmcnt(0)
	s_and_saveexec_b64 vcc, s[2:3]
	v_add_f32_e32 v180, v180, v169
	v_fma_f32 v180, v180, s66, 0.5
	v_trunc_f32_e32 v180, v180
	v_mul_f32_e32 v181, 0x2f800000, v180
	v_floor_f32_e32 v181, v181
	v_fmac_f32_e32 v180, 0xcf800000, v181
	v_cvt_u32_f32_e32 v181, v181
	v_cvt_u32_f32_e32 v180, v180
	v_add_u32_e32 v181, 0x10000, v181
	global_atomic_add_x2 v[178:179], v[180:181], off offset:1152
	s_mov_b64 exec, vcc
	s_waitcnt vmcnt(9)
	v_lshlrev_b32_e32 v160, 16, v77
	v_and_b32_e32 v161, 0xffff0000, v77
	v_and_b32_e32 v77, 0xffff0000, v76
	v_lshlrev_b32_e32 v76, 16, v76
	v_lshlrev_b32_e32 v162, 16, v79
	v_and_b32_e32 v163, 0xffff0000, v79
	v_and_b32_e32 v79, 0xffff0000, v78
	v_lshlrev_b32_e32 v78, 16, v78
	v_pk_fma_f32 v[28:29], v[154:155], v[76:77], v[28:29] op_sel_hi:[0,1,1]
	v_pk_fma_f32 v[30:31], v[154:155], v[160:161], v[30:31] op_sel_hi:[0,1,1]
	v_pk_fma_f32 v[24:25], v[154:155], v[78:79], v[24:25] op_sel_hi:[0,1,1]
	v_pk_fma_f32 v[26:27], v[154:155], v[162:163], v[26:27] op_sel_hi:[0,1,1]
	v_mul_f32_e32 v168, v29, v29
	v_mul_f32_e32 v169, v31, v31
	v_fmac_f32_e32 v168, v28, v28
	v_fmac_f32_e32 v169, v30, v30
	v_add_f32_e32 v168, v168, v169
	v_mul_f32_e32 v169, v25, v25
	v_fmac_f32_e32 v169, v24, v24
	v_add_f32_e32 v168, v169, v168
	v_mul_f32_e32 v169, v27, v27
	v_fmac_f32_e32 v169, v26, v26
	v_add_f32_e32 v153, v169, v168
	v_cvt_pk_bf16_f32 v76, v28, v29
	v_cvt_pk_bf16_f32 v77, v30, v31
	v_cvt_pk_bf16_f32 v78, v24, v25
	v_cvt_pk_bf16_f32 v79, v26, v27
	global_store_dwordx4 v[174:175], v[76:79], off
	v_lshlrev_b32_e32 v160, 16, v69
	v_and_b32_e32 v161, 0xffff0000, v69
	v_and_b32_e32 v69, 0xffff0000, v68
	v_lshlrev_b32_e32 v68, 16, v68
	v_lshlrev_b32_e32 v162, 16, v71
	v_and_b32_e32 v163, 0xffff0000, v71
	v_and_b32_e32 v71, 0xffff0000, v70
	v_lshlrev_b32_e32 v70, 16, v70
	v_pk_fma_f32 v[20:21], v[154:155], v[68:69], v[20:21] op_sel_hi:[0,1,1]
	v_pk_fma_f32 v[22:23], v[154:155], v[160:161], v[22:23] op_sel_hi:[0,1,1]
	v_pk_fma_f32 v[16:17], v[154:155], v[70:71], v[16:17] op_sel_hi:[0,1,1]
	v_pk_fma_f32 v[18:19], v[154:155], v[162:163], v[18:19] op_sel_hi:[0,1,1]
	v_mul_f32_e32 v168, v21, v21
	v_mul_f32_e32 v169, v23, v23
	v_fmac_f32_e32 v168, v20, v20
	v_fmac_f32_e32 v169, v22, v22
	v_add_f32_e32 v168, v168, v169
	v_mul_f32_e32 v169, v17, v17
	v_fmac_f32_e32 v169, v16, v16
	v_add_f32_e32 v168, v169, v168
	v_mul_f32_e32 v169, v19, v19
	v_fmac_f32_e32 v169, v18, v18
	v_add_f32_e32 v180, v169, v168
	v_cvt_pk_bf16_f32 v68, v20, v21
	v_cvt_pk_bf16_f32 v69, v22, v23
	v_cvt_pk_bf16_f32 v70, v16, v17
	v_cvt_pk_bf16_f32 v71, v18, v19
	global_store_dwordx4 v[174:175], v[68:71], off offset:256
	v_add_f32_e32 v180, v153, v180
	ds_bpermute_b32 v169, v156, v180
	v_lshl_add_u64 v[174:175], v[174:175], 0, s[50:51]
	s_waitcnt lgkmcnt(0)
; __device__ __forceinline__ unsigned cvt_pk_bf16(float lo, float hi) { unsigned r; asm volatile("v_cvt_pk_bf16_f32 %0, %1, %2" : "=v"(r) : "v"(lo), "v"(hi)); return r; }
; template <class Epi, class Sched, bool ALIGN_EPI = false, bool SP2 = false>
; __device__ __forceinline__ void gemm_phase(PG8_LAS unsigned char* lds, const Gemm g, const Sched& S, const Epi& E) {
;     ...
;         if constexpr (!Epi::AFTER_DRAIN) { if constexpr (epi_prefetches<Epi>::value) E(acc, cur, wr, wc, fr, fq, ui); else E(acc, cur, wr, wc, fr, fq); S.done(cur); }
;         if (!has_next) break;
;     __device__ __forceinline__ void operator()(const f32x4 (&acc)[2][2][4][2], const Unit& u, int wr, int wc, int fr, int fq) const {
;     ...
;         for (int st = 0; st < 8; ++st) { const int ai = st >> 2, m = st & 3; const int row = row0 + ai * HALF + m * 16;
;             if (st < 7) { const int rn = row0 + ((st + 1) >> 2) * HALF + ((st + 1) & 3) * 16; const size_t off = (size_t)rn * 1024 + col0; u32x4* p = pre[(st + 1) & 1];
;                 p[0] = *(const u32x4*)(xb + off); p[1] = *(const u32x4*)(xb + off + HALF); }
;             __builtin_amdgcn_sched_barrier(0);
;             float s = 0.f; const float r = rs[st];
; #pragma unroll
;             for (int bj = 0; bj < 2; ++bj) { const size_t off = (size_t)row * 1024 + col0 + bj * HALF; const u32x4 h = pre[st & 1][bj];
;                 const f32x4 x0 = (f32x4){__uint_as_float(h.x << 16), __uint_as_float(h.x & 0xffff0000u), __uint_as_float(h.y << 16), __uint_as_float(h.y & 0xffff0000u)};
;                 const f32x4 x1v = (f32x4){__uint_as_float(h.z << 16), __uint_as_float(h.z & 0xffff0000u), __uint_as_float(h.w << 16), __uint_as_float(h.w & 0xffff0000u)};
;                 const f32x4 v0 = acc[ai][bj][m][0] + x0 * r, v1 = acc[ai][bj][m][1] + x1v * r;
;                 u32x4 w; w.x = cvt_pk_bf16(v0[0], v0[1]); w.y = cvt_pk_bf16(v0[2], v0[3]); w.z = cvt_pk_bf16(v1[0], v1[1]); w.w = cvt_pk_bf16(v1[2], v1[3]);
;                 *(u32x4*)(xb + off) = w;
;                 s += (v0[0] * v0[0] + v0[1] * v0[1]) + (v0[2] * v0[2] + v0[3] * v0[3]) + (v1[0] * v1[0] + v1[1] * v1[1]) + (v1[2] * v1[2] + v1[3] * v1[3]); }
;             s += __shfl_xor(s, 16); s += __shfl_xor(s, 32);
;             if (fq == 0) (void)__hip_atomic_fetch_add(racc + row, (1ull << 48) + (unsigned long long)(s * 65536.0f + 0.5f), __ATOMIC_RELAXED, __HIP_MEMORY_SCOPE_AGENT);
	v_add_f32_e32 v180, v180, v169
	ds_bpermute_b32 v169, v157, v180
	s_waitcnt lgkmcnt(0)
	s_and_saveexec_b64 vcc, s[2:3]
	v_add_f32_e32 v180, v180, v169
	v_fma_f32 v180, v180, s66, 0.5
	v_trunc_f32_e32 v180, v180
	v_mul_f32_e32 v181, 0x2f800000, v180
	v_floor_f32_e32 v181, v181
	v_fmac_f32_e32 v180, 0xcf800000, v181
	v_cvt_u32_f32_e32 v181, v181
	v_cvt_u32_f32_e32 v180, v180
	v_add_u32_e32 v181, 0x10000, v181
	global_atomic_add_x2 v[178:179], v[180:181], off offset:1280
	s_mov_b64 exec, vcc
	s_waitcnt vmcnt(7)
	v_lshlrev_b32_e32 v160, 16, v61
	v_and_b32_e32 v161, 0xffff0000, v61
	v_and_b32_e32 v61, 0xffff0000, v60
	v_lshlrev_b32_e32 v60, 16, v60
	v_lshlrev_b32_e32 v162, 16, v63
	v_and_b32_e32 v163, 0xffff0000, v63
	v_and_b32_e32 v63, 0xffff0000, v62
	v_lshlrev_b32_e32 v62, 16, v62
	v_pk_fma_f32 v[12:13], v[158:159], v[60:61], v[12:13] op_sel_hi:[0,1,1]
	v_pk_fma_f32 v[14:15], v[158:159], v[160:161], v[14:15] op_sel_hi:[0,1,1]
	v_pk_fma_f32 v[8:9], v[158:159], v[62:63], v[8:9] op_sel_hi:[0,1,1]
	v_pk_fma_f32 v[10:11], v[158:159], v[162:163], v[10:11] op_sel_hi:[0,1,1]
	v_mul_f32_e32 v168, v13, v13
	v_mul_f32_e32 v169, v15, v15
	v_fmac_f32_e32 v168, v12, v12
	v_fmac_f32_e32 v169, v14, v14
	v_add_f32_e32 v168, v168, v169
	v_mul_f32_e32 v169, v9, v9
	v_fmac_f32_e32 v169, v8, v8
	v_add_f32_e32 v168, v169, v168
	v_mul_f32_e32 v169, v11, v11
	v_fmac_f32_e32 v169, v10, v10
	v_add_f32_e32 v153, v169, v168
	v_cvt_pk_bf16_f32 v60, v12, v13
	v_cvt_pk_bf16_f32 v61, v14, v15
	v_cvt_pk_bf16_f32 v62, v8, v9
	v_cvt_pk_bf16_f32 v63, v10, v11
	global_store_dwordx4 v[174:175], v[60:63], off
	v_lshlrev_b32_e32 v160, 16, v53
	v_and_b32_e32 v161, 0xffff0000, v53
	v_and_b32_e32 v53, 0xffff0000, v52
	v_lshlrev_b32_e32 v52, 16, v52
	v_lshlrev_b32_e32 v162, 16, v55
	v_and_b32_e32 v163, 0xffff0000, v55
	v_and_b32_e32 v55, 0xffff0000, v54
	v_lshlrev_b32_e32 v54, 16, v54
	v_pk_fma_f32 v[4:5], v[158:159], v[52:53], v[4:5] op_sel_hi:[0,1,1]
	v_pk_fma_f32 v[6:7], v[158:159], v[160:161], v[6:7] op_sel_hi:[0,1,1]
	v_pk_fma_f32 v[0:1], v[158:159], v[54:55], v[0:1] op_sel_hi:[0,1,1]
	v_pk_fma_f32 v[2:3], v[158:159], v[162:163], v[2:3] op_sel_hi:[0,1,1]
	v_mul_f32_e32 v168, v5, v5
	v_mul_f32_e32 v169, v7, v7
	v_fmac_f32_e32 v168, v4, v4
	v_fmac_f32_e32 v169, v6, v6
	v_add_f32_e32 v168, v168, v169
	v_mul_f32_e32 v169, v1, v1
	v_fmac_f32_e32 v169, v0, v0
	v_add_f32_e32 v168, v169, v168
	v_mul_f32_e32 v169, v3, v3
	v_fmac_f32_e32 v169, v2, v2
	v_add_f32_e32 v180, v169, v168
	v_cvt_pk_bf16_f32 v52, v4, v5
	v_cvt_pk_bf16_f32 v53, v6, v7
	v_cvt_pk_bf16_f32 v54, v0, v1
	v_cvt_pk_bf16_f32 v55, v2, v3
	global_store_dwordx4 v[174:175], v[52:55], off offset:256
	v_add_f32_e32 v180, v153, v180
	ds_bpermute_b32 v169, v156, v180
	s_waitcnt lgkmcnt(0)
	v_add_f32_e32 v180, v180, v169
	ds_bpermute_b32 v169, v157, v180
	s_waitcnt lgkmcnt(0)
	s_and_saveexec_b64 vcc, s[2:3]
	v_add_f32_e32 v180, v180, v169
	v_fma_f32 v180, v180, s66, 0.5
	v_trunc_f32_e32 v180, v180
	v_mul_f32_e32 v181, 0x2f800000, v180
	v_floor_f32_e32 v181, v181
	v_fmac_f32_e32 v180, 0xcf800000, v181
	v_cvt_u32_f32_e32 v181, v181
	v_cvt_u32_f32_e32 v180, v180
	v_add_u32_e32 v181, 0x10000, v181
	global_atomic_add_x2 v[178:179], v[180:181], off offset:1408
	s_mov_b64 exec, vcc
	s_andn2_b64 vcc, exec, s[4:5]
	s_mov_b64 s[4:5], -1
	s_cbranch_vccnz .LBB0_472
	s_andn2_b64 vcc, exec, s[6:7]
	s_cbranch_vccnz .LBB0_471
	s_barrier
	s_branch .LBB0_471
